# grid-barrier poll sleep 32 (was 20)
# baseline (speedup 1.0000x reference)
.LBB0_37:
	s_sleep 32
	global_load_dword v1, v0, s[8:9] sc1
	s_waitcnt vmcnt(0)
	v_cmp_gt_u32_e32 vcc, s2, v1
	s_cbranch_vccnz .LBB0_37

.LBB0_113:
	s_sleep 32
	global_load_dword v1, v0, s[10:11] sc1
	s_waitcnt vmcnt(0)
	v_cmp_gt_u32_e32 vcc, s2, v1
	s_cbranch_vccnz .LBB0_113

.LBB0_151:
	s_sleep 32
	global_load_dword v1, v0, s[6:7] sc1
	s_waitcnt vmcnt(0)
	v_cmp_gt_u32_e32 vcc, s2, v1
	s_cbranch_vccnz .LBB0_151

.LBB0_613:
	s_sleep 32
	global_load_dword v1, v0, s[10:11] sc1
	s_waitcnt vmcnt(0)
	v_cmp_gt_u32_e32 vcc, s3, v1
	s_cbranch_vccnz .LBB0_613

.Lfb_poll:
	global_load_dword v1, v0, s[10:11] offset:512 sc1
	s_waitcnt vmcnt(0)
	v_cmp_gt_u32_e32 vcc, 8, v1
	s_cbranch_vccz .Lfb_done
	s_sleep 32
	s_branch .Lfb_poll

.LBB0_702:
	s_sleep 32
	global_load_dword v1, v0, s[10:11] sc1
	s_waitcnt vmcnt(0)
	v_cmp_gt_u32_e32 vcc, s7, v1
	s_cbranch_vccnz .LBB0_702
